# GU epilogue hand-rewritten: 6 VALU per element, 32-bit store offsets
# speedup vs baseline: 1.1911x; 1.1911x over previous
.LBB0_1255:
	s_lshl_b32 s6, s48, 8
	s_add_i32 s6, s6, s91
	s_lshl_b32 s22, s49, 7
	s_ashr_i32 s23, s22, 31
	s_add_u32 s24, s2, s22
	s_addc_u32 s25, s3, s23
	s_add_u32 s24, s24, s68
	s_addc_u32 s25, s25, s69
	s_mov_b32 s98, 0x44800000
	s_mov_b32 s99, 0xbd38aa3b
	v_and_or_b32 v4, v174, 15, s6
	v_lshrrev_b32_e32 v0, 4, v174
	v_mul_lo_u32 v4, v4, s42
	v_lshl_add_u32 v4, v0, 3, v4
	v_mul_f32_e32 v8, s99, v156
	v_mul_f32_e32 v9, s99, v157
	v_mul_f32_e32 v10, s99, v158
	v_mul_f32_e32 v11, s99, v159
	v_mul_f32_e32 v12, s99, v152
	v_mul_f32_e32 v13, s99, v153
	v_mul_f32_e32 v14, s99, v154
	v_mul_f32_e32 v15, s99, v155
	v_exp_f32_e32 v8, v8
	v_exp_f32_e32 v9, v9
	v_exp_f32_e32 v10, v10
	v_exp_f32_e32 v11, v11
	v_exp_f32_e32 v12, v12
	v_exp_f32_e32 v13, v13
	v_exp_f32_e32 v14, v14
	v_exp_f32_e32 v15, v15
	v_fma_f32 v8, v8, s98, s98
	v_fma_f32 v9, v9, s98, s98
	v_fma_f32 v10, v10, s98, s98
	v_fma_f32 v11, v11, s98, s98
	v_fma_f32 v12, v12, s98, s98
	v_fma_f32 v13, v13, s98, s98
	v_fma_f32 v14, v14, s98, s98
	v_fma_f32 v15, v15, s98, s98
	v_rcp_f32_e32 v8, v8
	v_rcp_f32_e32 v9, v9
	v_rcp_f32_e32 v10, v10
	v_rcp_f32_e32 v11, v11
	v_rcp_f32_e32 v12, v12
	v_rcp_f32_e32 v13, v13
	v_rcp_f32_e32 v14, v14
	v_rcp_f32_e32 v15, v15
	v_mul_f32_e32 v8, v156, v8
	v_mul_f32_e32 v9, v157, v9
	v_mul_f32_e32 v10, v158, v10
	v_mul_f32_e32 v11, v159, v11
	v_mul_f32_e32 v12, v152, v12
	v_mul_f32_e32 v13, v153, v13
	v_mul_f32_e32 v14, v154, v14
	v_mul_f32_e32 v15, v155, v15
	v_mul_f32_e32 v8, v8, v148
	v_mul_f32_e32 v9, v9, v149
	v_mul_f32_e32 v10, v10, v150
	v_mul_f32_e32 v11, v11, v151
	v_mul_f32_e32 v12, v12, v144
	v_mul_f32_e32 v13, v13, v145
	v_mul_f32_e32 v14, v14, v146
	v_mul_f32_e32 v15, v15, v147
	v_cvt_pk_fp8_f32 v6, v8, v9
	v_cvt_pk_fp8_f32 v7, v12, v13
	v_cvt_pk_fp8_f32 v6, v10, v11 op_sel:[0,0,1]
	v_cvt_pk_fp8_f32 v7, v14, v15 op_sel:[0,0,1]
	s_nop 0
	global_store_dwordx2 v4, v[6:7], s[24:25]
	v_add_u32_e32 v4, 0xb000, v4
	v_mul_f32_e32 v8, s99, v140
	v_mul_f32_e32 v9, s99, v141
	v_mul_f32_e32 v10, s99, v142
	v_mul_f32_e32 v11, s99, v143
	v_mul_f32_e32 v12, s99, v136
	v_mul_f32_e32 v13, s99, v137
	v_mul_f32_e32 v14, s99, v138
	v_mul_f32_e32 v15, s99, v139
	v_exp_f32_e32 v8, v8
	v_exp_f32_e32 v9, v9
	v_exp_f32_e32 v10, v10
	v_exp_f32_e32 v11, v11
	v_exp_f32_e32 v12, v12
	v_exp_f32_e32 v13, v13
	v_exp_f32_e32 v14, v14
	v_exp_f32_e32 v15, v15
	v_fma_f32 v8, v8, s98, s98
	v_fma_f32 v9, v9, s98, s98
	v_fma_f32 v10, v10, s98, s98
	v_fma_f32 v11, v11, s98, s98
	v_fma_f32 v12, v12, s98, s98
	v_fma_f32 v13, v13, s98, s98
	v_fma_f32 v14, v14, s98, s98
	v_fma_f32 v15, v15, s98, s98
	v_rcp_f32_e32 v8, v8
	v_rcp_f32_e32 v9, v9
	v_rcp_f32_e32 v10, v10
	v_rcp_f32_e32 v11, v11
	v_rcp_f32_e32 v12, v12
	v_rcp_f32_e32 v13, v13
	v_rcp_f32_e32 v14, v14
	v_rcp_f32_e32 v15, v15
	v_mul_f32_e32 v8, v140, v8
	v_mul_f32_e32 v9, v141, v9
	v_mul_f32_e32 v10, v142, v10
	v_mul_f32_e32 v11, v143, v11
	v_mul_f32_e32 v12, v136, v12
	v_mul_f32_e32 v13, v137, v13
	v_mul_f32_e32 v14, v138, v14
	v_mul_f32_e32 v15, v139, v15
	v_mul_f32_e32 v8, v8, v132
	v_mul_f32_e32 v9, v9, v133
	v_mul_f32_e32 v10, v10, v134
	v_mul_f32_e32 v11, v11, v135
	v_mul_f32_e32 v12, v12, v128
	v_mul_f32_e32 v13, v13, v129
	v_mul_f32_e32 v14, v14, v130
	v_mul_f32_e32 v15, v15, v131
	v_cvt_pk_fp8_f32 v6, v8, v9
	v_cvt_pk_fp8_f32 v7, v12, v13
	v_cvt_pk_fp8_f32 v6, v10, v11 op_sel:[0,0,1]
	v_cvt_pk_fp8_f32 v7, v14, v15 op_sel:[0,0,1]
	s_nop 0
	global_store_dwordx2 v4, v[6:7], s[24:25]
	v_add_u32_e32 v4, 0xb000, v4
	v_mul_f32_e32 v8, s99, v124
	v_mul_f32_e32 v9, s99, v125
	v_mul_f32_e32 v10, s99, v126
	v_mul_f32_e32 v11, s99, v127
	v_mul_f32_e32 v12, s99, v120
	v_mul_f32_e32 v13, s99, v121
	v_mul_f32_e32 v14, s99, v122
	v_mul_f32_e32 v15, s99, v123
	v_exp_f32_e32 v8, v8
	v_exp_f32_e32 v9, v9
	v_exp_f32_e32 v10, v10
	v_exp_f32_e32 v11, v11
	v_exp_f32_e32 v12, v12
	v_exp_f32_e32 v13, v13
	v_exp_f32_e32 v14, v14
	v_exp_f32_e32 v15, v15
	v_fma_f32 v8, v8, s98, s98
	v_fma_f32 v9, v9, s98, s98
	v_fma_f32 v10, v10, s98, s98
	v_fma_f32 v11, v11, s98, s98
	v_fma_f32 v12, v12, s98, s98
	v_fma_f32 v13, v13, s98, s98
	v_fma_f32 v14, v14, s98, s98
	v_fma_f32 v15, v15, s98, s98
	v_rcp_f32_e32 v8, v8
	v_rcp_f32_e32 v9, v9
	v_rcp_f32_e32 v10, v10
	v_rcp_f32_e32 v11, v11
	v_rcp_f32_e32 v12, v12
	v_rcp_f32_e32 v13, v13
	v_rcp_f32_e32 v14, v14
	v_rcp_f32_e32 v15, v15
	v_mul_f32_e32 v8, v124, v8
	v_mul_f32_e32 v9, v125, v9
	v_mul_f32_e32 v10, v126, v10
	v_mul_f32_e32 v11, v127, v11
	v_mul_f32_e32 v12, v120, v12
	v_mul_f32_e32 v13, v121, v13
	v_mul_f32_e32 v14, v122, v14
	v_mul_f32_e32 v15, v123, v15
	v_mul_f32_e32 v8, v8, v116
	v_mul_f32_e32 v9, v9, v117
	v_mul_f32_e32 v10, v10, v118
	v_mul_f32_e32 v11, v11, v119
	v_mul_f32_e32 v12, v12, v112
	v_mul_f32_e32 v13, v13, v113
	v_mul_f32_e32 v14, v14, v114
	v_mul_f32_e32 v15, v15, v115
	v_cvt_pk_fp8_f32 v6, v8, v9
	v_cvt_pk_fp8_f32 v7, v12, v13
	v_cvt_pk_fp8_f32 v6, v10, v11 op_sel:[0,0,1]
	v_cvt_pk_fp8_f32 v7, v14, v15 op_sel:[0,0,1]
	s_nop 0
	global_store_dwordx2 v4, v[6:7], s[24:25]
	v_add_u32_e32 v4, 0xb000, v4
	v_mul_f32_e32 v8, s99, v108
	v_mul_f32_e32 v9, s99, v109
	v_mul_f32_e32 v10, s99, v110
	v_mul_f32_e32 v11, s99, v111
	v_mul_f32_e32 v12, s99, v104
	v_mul_f32_e32 v13, s99, v105
	v_mul_f32_e32 v14, s99, v106
	v_mul_f32_e32 v15, s99, v107
	v_exp_f32_e32 v8, v8
	v_exp_f32_e32 v9, v9
	v_exp_f32_e32 v10, v10
	v_exp_f32_e32 v11, v11
	v_exp_f32_e32 v12, v12
	v_exp_f32_e32 v13, v13
	v_exp_f32_e32 v14, v14
	v_exp_f32_e32 v15, v15
	v_fma_f32 v8, v8, s98, s98
	v_fma_f32 v9, v9, s98, s98
	v_fma_f32 v10, v10, s98, s98
	v_fma_f32 v11, v11, s98, s98
	v_fma_f32 v12, v12, s98, s98
	v_fma_f32 v13, v13, s98, s98
	v_fma_f32 v14, v14, s98, s98
	v_fma_f32 v15, v15, s98, s98
	v_rcp_f32_e32 v8, v8
	v_rcp_f32_e32 v9, v9
	v_rcp_f32_e32 v10, v10
	v_rcp_f32_e32 v11, v11
	v_rcp_f32_e32 v12, v12
	v_rcp_f32_e32 v13, v13
	v_rcp_f32_e32 v14, v14
	v_rcp_f32_e32 v15, v15
	v_mul_f32_e32 v8, v108, v8
	v_mul_f32_e32 v9, v109, v9
	v_mul_f32_e32 v10, v110, v10
	v_mul_f32_e32 v11, v111, v11
	v_mul_f32_e32 v12, v104, v12
	v_mul_f32_e32 v13, v105, v13
	v_mul_f32_e32 v14, v106, v14
	v_mul_f32_e32 v15, v107, v15
	v_mul_f32_e32 v8, v8, v100
	v_mul_f32_e32 v9, v9, v101
	v_mul_f32_e32 v10, v10, v102
	v_mul_f32_e32 v11, v11, v103
	v_mul_f32_e32 v12, v12, v96
	v_mul_f32_e32 v13, v13, v97
	v_mul_f32_e32 v14, v14, v98
	v_mul_f32_e32 v15, v15, v99
	v_cvt_pk_fp8_f32 v6, v8, v9
	v_cvt_pk_fp8_f32 v7, v12, v13
	v_cvt_pk_fp8_f32 v6, v10, v11 op_sel:[0,0,1]
	v_cvt_pk_fp8_f32 v7, v14, v15 op_sel:[0,0,1]
	s_nop 0
	global_store_dwordx2 v4, v[6:7], s[24:25]
	v_add_u32_e32 v4, 0x37000, v4
	v_mul_f32_e32 v8, s99, v92
	v_mul_f32_e32 v9, s99, v93
	v_mul_f32_e32 v10, s99, v94
	v_mul_f32_e32 v11, s99, v95
	v_mul_f32_e32 v12, s99, v88
	v_mul_f32_e32 v13, s99, v89
	v_mul_f32_e32 v14, s99, v90
	v_mul_f32_e32 v15, s99, v91
	v_exp_f32_e32 v8, v8
	v_exp_f32_e32 v9, v9
	v_exp_f32_e32 v10, v10
	v_exp_f32_e32 v11, v11
	v_exp_f32_e32 v12, v12
	v_exp_f32_e32 v13, v13
	v_exp_f32_e32 v14, v14
	v_exp_f32_e32 v15, v15
	v_fma_f32 v8, v8, s98, s98
	v_fma_f32 v9, v9, s98, s98
	v_fma_f32 v10, v10, s98, s98
	v_fma_f32 v11, v11, s98, s98
	v_fma_f32 v12, v12, s98, s98
	v_fma_f32 v13, v13, s98, s98
	v_fma_f32 v14, v14, s98, s98
	v_fma_f32 v15, v15, s98, s98
	v_rcp_f32_e32 v8, v8
	v_rcp_f32_e32 v9, v9
	v_rcp_f32_e32 v10, v10
	v_rcp_f32_e32 v11, v11
	v_rcp_f32_e32 v12, v12
	v_rcp_f32_e32 v13, v13
	v_rcp_f32_e32 v14, v14
	v_rcp_f32_e32 v15, v15
	v_mul_f32_e32 v8, v92, v8
	v_mul_f32_e32 v9, v93, v9
	v_mul_f32_e32 v10, v94, v10
	v_mul_f32_e32 v11, v95, v11
	v_mul_f32_e32 v12, v88, v12
	v_mul_f32_e32 v13, v89, v13
	v_mul_f32_e32 v14, v90, v14
	v_mul_f32_e32 v15, v91, v15
	v_mul_f32_e32 v8, v8, v84
	v_mul_f32_e32 v9, v9, v85
	v_mul_f32_e32 v10, v10, v86
	v_mul_f32_e32 v11, v11, v87
	v_mul_f32_e32 v12, v12, v80
	v_mul_f32_e32 v13, v13, v81
	v_mul_f32_e32 v14, v14, v82
	v_mul_f32_e32 v15, v15, v83
	v_cvt_pk_fp8_f32 v6, v8, v9
	v_cvt_pk_fp8_f32 v7, v12, v13
	v_cvt_pk_fp8_f32 v6, v10, v11 op_sel:[0,0,1]
	v_cvt_pk_fp8_f32 v7, v14, v15 op_sel:[0,0,1]
	s_nop 0
	global_store_dwordx2 v4, v[6:7], s[24:25]
	v_add_u32_e32 v4, 0xb000, v4
	v_mul_f32_e32 v8, s99, v76
	v_mul_f32_e32 v9, s99, v77
	v_mul_f32_e32 v10, s99, v78
	v_mul_f32_e32 v11, s99, v79
	v_mul_f32_e32 v12, s99, v72
	v_mul_f32_e32 v13, s99, v73
	v_mul_f32_e32 v14, s99, v74
	v_mul_f32_e32 v15, s99, v75
	v_exp_f32_e32 v8, v8
	v_exp_f32_e32 v9, v9
	v_exp_f32_e32 v10, v10
	v_exp_f32_e32 v11, v11
	v_exp_f32_e32 v12, v12
	v_exp_f32_e32 v13, v13
	v_exp_f32_e32 v14, v14
	v_exp_f32_e32 v15, v15
	v_fma_f32 v8, v8, s98, s98
	v_fma_f32 v9, v9, s98, s98
	v_fma_f32 v10, v10, s98, s98
	v_fma_f32 v11, v11, s98, s98
	v_fma_f32 v12, v12, s98, s98
	v_fma_f32 v13, v13, s98, s98
	v_fma_f32 v14, v14, s98, s98
	v_fma_f32 v15, v15, s98, s98
	v_rcp_f32_e32 v8, v8
	v_rcp_f32_e32 v9, v9
	v_rcp_f32_e32 v10, v10
	v_rcp_f32_e32 v11, v11
	v_rcp_f32_e32 v12, v12
	v_rcp_f32_e32 v13, v13
	v_rcp_f32_e32 v14, v14
	v_rcp_f32_e32 v15, v15
	v_mul_f32_e32 v8, v76, v8
	v_mul_f32_e32 v9, v77, v9
	v_mul_f32_e32 v10, v78, v10
	v_mul_f32_e32 v11, v79, v11
	v_mul_f32_e32 v12, v72, v12
	v_mul_f32_e32 v13, v73, v13
	v_mul_f32_e32 v14, v74, v14
	v_mul_f32_e32 v15, v75, v15
	v_mul_f32_e32 v8, v8, v68
	v_mul_f32_e32 v9, v9, v69
	v_mul_f32_e32 v10, v10, v70
	v_mul_f32_e32 v11, v11, v71
	v_mul_f32_e32 v12, v12, v64
	v_mul_f32_e32 v13, v13, v65
	v_mul_f32_e32 v14, v14, v66
	v_mul_f32_e32 v15, v15, v67
	v_cvt_pk_fp8_f32 v6, v8, v9
	v_cvt_pk_fp8_f32 v7, v12, v13
	v_cvt_pk_fp8_f32 v6, v10, v11 op_sel:[0,0,1]
	v_cvt_pk_fp8_f32 v7, v14, v15 op_sel:[0,0,1]
	s_nop 0
	global_store_dwordx2 v4, v[6:7], s[24:25]
	v_add_u32_e32 v4, 0xb000, v4
	v_mul_f32_e32 v8, s99, v60
	v_mul_f32_e32 v9, s99, v61
	v_mul_f32_e32 v10, s99, v62
	v_mul_f32_e32 v11, s99, v63
	v_mul_f32_e32 v12, s99, v56
	v_mul_f32_e32 v13, s99, v57
	v_mul_f32_e32 v14, s99, v58
	v_mul_f32_e32 v15, s99, v59
	v_exp_f32_e32 v8, v8
	v_exp_f32_e32 v9, v9
	v_exp_f32_e32 v10, v10
	v_exp_f32_e32 v11, v11
	v_exp_f32_e32 v12, v12
	v_exp_f32_e32 v13, v13
	v_exp_f32_e32 v14, v14
	v_exp_f32_e32 v15, v15
	v_fma_f32 v8, v8, s98, s98
	v_fma_f32 v9, v9, s98, s98
	v_fma_f32 v10, v10, s98, s98
	v_fma_f32 v11, v11, s98, s98
	v_fma_f32 v12, v12, s98, s98
	v_fma_f32 v13, v13, s98, s98
	v_fma_f32 v14, v14, s98, s98
	v_fma_f32 v15, v15, s98, s98
	v_rcp_f32_e32 v8, v8
	v_rcp_f32_e32 v9, v9
	v_rcp_f32_e32 v10, v10
	v_rcp_f32_e32 v11, v11
	v_rcp_f32_e32 v12, v12
	v_rcp_f32_e32 v13, v13
	v_rcp_f32_e32 v14, v14
	v_rcp_f32_e32 v15, v15
	v_mul_f32_e32 v8, v60, v8
	v_mul_f32_e32 v9, v61, v9
	v_mul_f32_e32 v10, v62, v10
	v_mul_f32_e32 v11, v63, v11
	v_mul_f32_e32 v12, v56, v12
	v_mul_f32_e32 v13, v57, v13
	v_mul_f32_e32 v14, v58, v14
	v_mul_f32_e32 v15, v59, v15
	v_mul_f32_e32 v8, v8, v52
	v_mul_f32_e32 v9, v9, v53
	v_mul_f32_e32 v10, v10, v54
	v_mul_f32_e32 v11, v11, v55
	v_mul_f32_e32 v12, v12, v48
	v_mul_f32_e32 v13, v13, v49
	v_mul_f32_e32 v14, v14, v50
	v_mul_f32_e32 v15, v15, v51
	v_cvt_pk_fp8_f32 v6, v8, v9
	v_cvt_pk_fp8_f32 v7, v12, v13
	v_cvt_pk_fp8_f32 v6, v10, v11 op_sel:[0,0,1]
	v_cvt_pk_fp8_f32 v7, v14, v15 op_sel:[0,0,1]
	s_nop 0
	global_store_dwordx2 v4, v[6:7], s[24:25]
	v_add_u32_e32 v4, 0xb000, v4
	v_mul_f32_e32 v8, s99, v44
	v_mul_f32_e32 v9, s99, v45
	v_mul_f32_e32 v10, s99, v46
	v_mul_f32_e32 v11, s99, v47
	v_mul_f32_e32 v12, s99, v40
	v_mul_f32_e32 v13, s99, v41
	v_mul_f32_e32 v14, s99, v42
	v_mul_f32_e32 v15, s99, v43
	v_exp_f32_e32 v8, v8
	v_exp_f32_e32 v9, v9
	v_exp_f32_e32 v10, v10
	v_exp_f32_e32 v11, v11
	v_exp_f32_e32 v12, v12
	v_exp_f32_e32 v13, v13
	v_exp_f32_e32 v14, v14
	v_exp_f32_e32 v15, v15
	v_fma_f32 v8, v8, s98, s98
	v_fma_f32 v9, v9, s98, s98
	v_fma_f32 v10, v10, s98, s98
	v_fma_f32 v11, v11, s98, s98
	v_fma_f32 v12, v12, s98, s98
	v_fma_f32 v13, v13, s98, s98
	v_fma_f32 v14, v14, s98, s98
	v_fma_f32 v15, v15, s98, s98
	v_rcp_f32_e32 v8, v8
	v_rcp_f32_e32 v9, v9
	v_rcp_f32_e32 v10, v10
	v_rcp_f32_e32 v11, v11
	v_rcp_f32_e32 v12, v12
	v_rcp_f32_e32 v13, v13
	v_rcp_f32_e32 v14, v14
	v_rcp_f32_e32 v15, v15
	v_mul_f32_e32 v8, v44, v8
	v_mul_f32_e32 v9, v45, v9
	v_mul_f32_e32 v10, v46, v10
	v_mul_f32_e32 v11, v47, v11
	v_mul_f32_e32 v12, v40, v12
	v_mul_f32_e32 v13, v41, v13
	v_mul_f32_e32 v14, v42, v14
	v_mul_f32_e32 v15, v43, v15
	v_mul_f32_e32 v8, v8, v36
	v_mul_f32_e32 v9, v9, v37
	v_mul_f32_e32 v10, v10, v38
	v_mul_f32_e32 v11, v11, v39
	v_mul_f32_e32 v12, v12, v32
	v_mul_f32_e32 v13, v13, v33
	v_mul_f32_e32 v14, v14, v34
	v_mul_f32_e32 v15, v15, v35
	v_cvt_pk_fp8_f32 v6, v8, v9
	v_cvt_pk_fp8_f32 v7, v12, v13
	v_cvt_pk_fp8_f32 v6, v10, v11 op_sel:[0,0,1]
	v_cvt_pk_fp8_f32 v7, v14, v15 op_sel:[0,0,1]
	s_nop 0
	global_store_dwordx2 v4, v[6:7], s[24:25]
	s_andn2_b64 vcc, exec, s[18:19]
	s_mov_b64 s[18:19], -1
	s_cbranch_vccnz .LBB0_1244
	s_andn2_b64 vcc, exec, s[8:9]
	s_cbranch_vccnz .LBB0_1243
	s_barrier
	s_branch .LBB0_1243

	.amdhsa_kernel _Z14fwd_megakernel6Params
		.amdhsa_group_segment_fixed_size 0
		.amdhsa_private_segment_fixed_size 0
		.amdhsa_kernarg_size 416
		.amdhsa_user_sgpr_count 2
		.amdhsa_user_sgpr_dispatch_ptr 0
		.amdhsa_user_sgpr_queue_ptr 0
		.amdhsa_user_sgpr_kernarg_segment_ptr 1
		.amdhsa_user_sgpr_dispatch_id 0
		.amdhsa_user_sgpr_kernarg_preload_length 0
		.amdhsa_user_sgpr_kernarg_preload_offset 0
		.amdhsa_user_sgpr_private_segment_size 0
		.amdhsa_uses_dynamic_stack 0
		.amdhsa_enable_private_segment 0
		.amdhsa_system_sgpr_workgroup_id_x 1
		.amdhsa_system_sgpr_workgroup_id_y 0
		.amdhsa_system_sgpr_workgroup_id_z 0
		.amdhsa_system_sgpr_workgroup_info 0
		.amdhsa_system_vgpr_workitem_id 2
		.amdhsa_next_free_vgpr 256
		.amdhsa_next_free_sgpr 100
		.amdhsa_accum_offset 256
		.amdhsa_reserve_vcc 1
		.amdhsa_float_round_mode_32 0
		.amdhsa_float_round_mode_16_64 0
		.amdhsa_float_denorm_mode_32 3
		.amdhsa_float_denorm_mode_16_64 3
		.amdhsa_dx10_clamp 1
		.amdhsa_ieee_mode 1
		.amdhsa_fp16_overflow 0
		.amdhsa_tg_split 0
		.amdhsa_exception_fp_ieee_invalid_op 0
		.amdhsa_exception_fp_denorm_src 0
		.amdhsa_exception_fp_ieee_div_zero 0
		.amdhsa_exception_fp_ieee_overflow 0
		.amdhsa_exception_fp_ieee_underflow 0
		.amdhsa_exception_fp_ieee_inexact 0
		.amdhsa_exception_int_div_zero 0
	.end_amdhsa_kernel

amdhsa.kernels:
  - .agpr_count:     0
    .args:
      - .offset:         0
        .size:           160
        .value_kind:     by_value
      - .offset:         160
        .size:           4
        .value_kind:     hidden_block_count_x
      - .offset:         164
        .size:           4
        .value_kind:     hidden_block_count_y
      - .offset:         168
        .size:           4
        .value_kind:     hidden_block_count_z
      - .offset:         172
        .size:           2
        .value_kind:     hidden_group_size_x
      - .offset:         174
        .size:           2
        .value_kind:     hidden_group_size_y
      - .offset:         176
        .size:           2
        .value_kind:     hidden_group_size_z
      - .offset:         178
        .size:           2
        .value_kind:     hidden_remainder_x
      - .offset:         180
        .size:           2
        .value_kind:     hidden_remainder_y
      - .offset:         182
        .size:           2
        .value_kind:     hidden_remainder_z
      - .offset:         200
        .size:           8
        .value_kind:     hidden_global_offset_x
      - .offset:         208
        .size:           8
        .value_kind:     hidden_global_offset_y
      - .offset:         216
        .size:           8
        .value_kind:     hidden_global_offset_z
      - .offset:         224
        .size:           2
        .value_kind:     hidden_grid_dims
      - .offset:         248
        .size:           8
        .value_kind:     hidden_multigrid_sync_arg
      - .offset:         280
        .size:           4
        .value_kind:     hidden_dynamic_lds_size
    .group_segment_fixed_size: 0
    .kernarg_segment_align: 8
    .kernarg_segment_size: 416
    .language:       OpenCL C
    .language_version:
      - 2
      - 0
    .max_flat_workgroup_size: 512
    .name:           _Z14fwd_megakernel6Params
    .private_segment_fixed_size: 0
    .sgpr_count:     106
    .sgpr_spill_count: 185
    .symbol:         _Z14fwd_megakernel6Params.kd
    .uniform_work_group_size: 1
    .uses_dynamic_stack: false
    .vgpr_count:     256
    .vgpr_spill_count: 0
    .wavefront_size: 64
